# attention tile loop: static s_setprio 1 for the deferred wave group (waves 4-7)
# baseline (speedup 1.0000x reference)
; DEV unsigned cvt_pk_bf16(float lo, float hi) { unsigned r; asm volatile("v_cvt_pk_bf16_f32 %0, %1, %2" : "=v"(r) : "v"(lo), "v"(hi)); return r; }
; DEV void attn_item(LAS unsigned char* lds, const bf16_t* P, const bf16_t* QB, const bf16_t* KV, const bf16_t* KC, const bf16_t* VC, const float* rel_bias, bf16_t* OB, int b, int g, int qt) {
;     ...
; #pragma unroll
;     for (int hh = 0; hh < 2; ++hh)
; #pragma unroll
;         for (int dt = 0; dt < 4; ++dt) { u32x2 w; w.x = cvt_pk_bf16(F[hh][dt][0], F[hh][dt][1]); w.y = cvt_pk_bf16(F[hh][dt][2], F[hh][dt][3]);
;             *(u32x2*)(OB + tok * 1024 + (g * 4 + hp * 2 + hh) * 64 + dt * 16 + g4 * 4) = w; }
.LBB0_157:
	s_setprio 0
	v_lshl_add_u64 v[2:3], s[86:87], 0, v[96:97]
	v_lshlrev_b32_e32 v0, 1, v138
	v_lshl_add_u64 v[2:3], v[2:3], 0, v[0:1]
	v_lshlrev_b32_e32 v0, 1, v140
	v_lshl_add_u64 v[2:3], v[2:3], 0, v[0:1]
	v_cvt_pk_bf16_f32 v4, v134, v135
	v_cvt_pk_bf16_f32 v5, v130, v131
	global_store_dwordx2 v[2:3], v[4:5], off
	v_cvt_pk_bf16_f32 v4, v132, v133
	v_cvt_pk_bf16_f32 v5, v128, v129
	global_store_dwordx2 v[2:3], v[4:5], off offset:32
	v_cvt_pk_bf16_f32 v4, v124, v125
	v_cvt_pk_bf16_f32 v5, v120, v121
	global_store_dwordx2 v[2:3], v[4:5], off offset:64
	v_cvt_pk_bf16_f32 v4, v122, v123
	v_cvt_pk_bf16_f32 v5, v118, v119
	global_store_dwordx2 v[2:3], v[4:5], off offset:96
	v_cvt_pk_bf16_f32 v4, v116, v117
	v_cvt_pk_bf16_f32 v5, v114, v115
	global_store_dwordx2 v[2:3], v[4:5], off offset:128
	v_cvt_pk_bf16_f32 v4, v112, v113
	v_cvt_pk_bf16_f32 v5, v110, v111
	v_readlane_b32 s90, v254, 53
	v_readlane_b32 s92, v254, 55
	global_store_dwordx2 v[2:3], v[4:5], off offset:160
	v_cvt_pk_bf16_f32 v4, v108, v109
	v_cvt_pk_bf16_f32 v5, v104, v105
	v_readlane_b32 s91, v254, 54
	v_readlane_b32 s93, v254, 56
	s_movk_i32 s94, 0x80
	v_readlane_b32 s95, v254, 58
	s_movk_i32 s96, 0x204
	s_movk_i32 s97, 0xb80
	global_store_dwordx2 v[2:3], v[4:5], off offset:192
	v_cvt_pk_bf16_f32 v4, v106, v107
	v_cvt_pk_bf16_f32 v5, v102, v103
	global_store_dwordx2 v[2:3], v[4:5], off offset:224

; #define LAS __attribute__((address_space(3)))
; DEV void attn_item(LAS unsigned char* lds, const bf16_t* P, const bf16_t* QB, const bf16_t* KV, const bf16_t* KC, const bf16_t* VC, const float* rel_bias, bf16_t* OB, int b, int g, int qt) {
;     ...
;         const int cur = qt;
;         const unsigned forced = 1u | (1u << cur) | (cur > 0 ? (1u << (cur - 1)) : 0u);
;         const int need = 8 - __popc(forced);
;         for (int it = 0; it < 4; ++it) { const int q = wave * 8 + it * 2 + (lane >> 5), j = lane & 31;
;             const float v = IMPF[q * 32 + j]; int rank = 0;
;             for (int jp = 1; jp <= cur - 2; ++jp) { const float vp = IMPF[q * 32 + jp]; rank += (vp > v || (vp == v && jp < j)) ? 1 : 0; }
;             const bool sel = (j >= 1) && (j <= cur - 2) && (rank < need);
;             const unsigned long long bal = __ballot(sel);
;             const unsigned mq = forced | (unsigned)(lane < 32 ? bal : (bal >> 32));
;             if (j == 0) MASK[q] = mq; }
;     }
;     __syncthreads();
;     const unsigned mymask = MASK[qs * 16 + fr];
;     unsigned anym = MASK[lane];
; #pragma unroll
;     for (int o = 32; o >= 1; o >>= 1) anym |= __shfl_xor(anym, o);
;     anym = __builtin_amdgcn_readfirstlane(anym);
;     {
;         float cbias[2]; cbias[0] = *(const LAS float*)(lds + btb + 512); cbias[1] = *(const LAS float*)(lds + btb + 512 + 516);
;         float mrun[2] = {NEG_, NEG_}, lrun[2] = {0.f, 0.f}; f32x4 O[2][4];
; #pragma unroll
;         for (int hh = 0; hh < 2; ++hh)
; #pragma unroll
;             for (int dt = 0; dt < 4; ++dt) O[hh][dt] = (f32x4){0.f, 0.f, 0.f, 0.f};
;         unsigned rem = anym & (qt >= 31 ? 0xffffffffu : ((2u << qt) - 1u)); rem &= ~1u;
;         int mode = 1, j = 0, buf = 0;
;         for (;;) {
;             kv_store(lds, pre, buf, tid);
.Lrk_done:
	s_lshr_b32 s4, 0x80000000, s17
	s_lshl_b32 s5, 1, s64
	s_cmp_lg_u32 s17, 31
	s_cselect_b32 s5, s5, 0
	s_or_b32 s4, s4, s5
	s_or_b32 s92, s4, 1
	s_bcnt1_i32_b32 s4, s92
	s_sub_i32 s93, 8, s4
	v_cmp_ne_u32_e32 vcc, 0, v60
	v_cmp_ge_i32_e64 s[44:45], s36, v60
	v_and_b32_e32 v67, 32, v150
	v_lshl_add_u32 v68, v66, 2, 0
	s_and_b64 s[4:5], vcc, s[44:45]
	v_add_u32_e32 v68, 0x11c00, v68
	v_cmp_eq_u32_e64 s[42:43], 0, v60
	v_cmp_gt_i32_e32 vcc, s93, v74
	s_and_b64 vcc, s[4:5], vcc
	s_nop 0
	v_lshrrev_b64 v[78:79], v67, vcc
	v_or_b32_e32 v78, s92, v78
	v_cmp_gt_i32_e32 vcc, s93, v75
	s_and_b64 vcc, s[4:5], vcc
	s_nop 0
	v_lshrrev_b64 v[80:81], v67, vcc
	v_or_b32_e32 v80, s92, v80
	v_cmp_gt_i32_e32 vcc, s93, v76
	s_and_b64 vcc, s[4:5], vcc
	s_nop 0
	v_lshrrev_b64 v[82:83], v67, vcc
	v_or_b32_e32 v82, s92, v82
	v_cmp_gt_i32_e32 vcc, s93, v77
	s_and_b64 vcc, s[4:5], vcc
	s_nop 0
	v_lshrrev_b64 v[84:85], v67, vcc
	v_or_b32_e32 v84, s92, v84
	s_and_saveexec_b64 s[4:5], s[42:43]
	ds_write_b32 v68, v78
	ds_write_b32 v68, v80 offset:8
	ds_write_b32 v68, v82 offset:16
	ds_write_b32 v68, v84 offset:24
	s_or_b64 exec, exec, s[4:5]
	s_add_i32 s4, 0, 0x11c00
	v_lshl_add_u32 v7, v152, 2, s4
	s_waitcnt lgkmcnt(0)
	s_barrier
	ds_read_b32 v7, v7
	v_lshlrev_b32_e32 v60, 2, v137
	v_lshlrev_b32_e32 v61, 2, v136
	v_add3_u32 v60, s4, v60, v61
	ds_read_b32 v127, v60
	s_waitcnt lgkmcnt(1)
	ds_bpermute_b32 v61, v144, v7
	v_and_b32_e32 v60, 0xffff0000, v149
	v_lshlrev_b32_e32 v126, 16, v149
	s_lshl_b32 s5, 2, s15
	s_waitcnt lgkmcnt(1)
	v_pk_fma_f32 v[134:135], v[126:127], v[2:3], 0 op_sel_hi:[0,1,0]
	s_waitcnt lgkmcnt(0)
	v_or_b32_e32 v7, v61, v7
	v_pk_fma_f32 v[116:117], v[60:61], v[44:45], 0 op_sel_hi:[0,1,0]
	ds_bpermute_b32 v44, v143, v7
	v_xor_b32_e32 v3, 4, v213
	v_pk_fma_f32 v[130:131], v[126:127], v[4:5], 0 op_sel_hi:[0,1,0]
	v_pk_fma_f32 v[132:133], v[126:127], v[32:33], 0 op_sel_hi:[0,1,0]
	s_add_i32 s5, s5, -1
	s_waitcnt lgkmcnt(0)
	v_or_b32_e32 v7, v44, v7
	v_xor_b32_e32 v44, 8, v213
	v_cmp_lt_i32_e32 vcc, v44, v153
	s_and_b32 s5, s5, -2
	s_cmp_lt_u32 s15, 31
	v_cndmask_b32_e32 v44, v213, v44, vcc
	v_lshlrev_b32_e32 v44, 2, v44
	ds_bpermute_b32 v44, v44, v7
	v_cmp_lt_i32_e32 vcc, v3, v153
	s_cselect_b32 s5, s5, -2
	v_pk_fma_f32 v[114:115], v[60:61], v[46:47], 0 op_sel_hi:[0,1,0]
	v_cndmask_b32_e32 v3, v213, v3, vcc
	s_waitcnt lgkmcnt(0)
	v_or_b32_e32 v2, v44, v7
	v_lshlrev_b32_e32 v3, 2, v3
	ds_bpermute_b32 v3, v3, v2
	v_pk_fma_f32 v[110:111], v[60:61], v[50:51], 0 op_sel_hi:[0,1,0]
	v_pk_fma_f32 v[112:113], v[60:61], v[48:49], 0 op_sel_hi:[0,1,0]
	v_pk_fma_f32 v[104:105], v[60:61], v[54:55], 0 op_sel_hi:[0,1,0]
	v_pk_fma_f32 v[108:109], v[60:61], v[52:53], 0 op_sel_hi:[0,1,0]
	s_waitcnt lgkmcnt(0)
	v_or_b32_e32 v4, v3, v2
	v_xor_b32_e32 v2, 2, v213
	v_cmp_lt_i32_e32 vcc, v2, v153
	v_and_b32_e32 v3, 0xffff0000, v148
	v_pk_fma_f32 v[102:103], v[60:61], v[58:59], 0 op_sel_hi:[0,1,0]
	v_cndmask_b32_e32 v2, v213, v2, vcc
	v_lshlrev_b32_e32 v2, 2, v2
	ds_bpermute_b32 v5, v2, v4
	v_lshlrev_b32_e32 v2, 16, v148
	v_mov_b32_e32 v148, 0
	v_pk_fma_f32 v[106:107], v[60:61], v[56:57], 0 op_sel_hi:[0,1,0]
	v_pk_fma_f32 v[128:129], v[126:127], v[34:35], 0 op_sel_hi:[0,1,0]
	s_waitcnt lgkmcnt(0)
	v_or_b32_e32 v32, v5, v4
	v_xor_b32_e32 v4, 1, v213
	v_cmp_lt_i32_e32 vcc, v4, v153
	v_pk_fma_f32 v[120:121], v[126:127], v[38:39], 0 op_sel_hi:[0,1,0]
	v_pk_fma_f32 v[124:125], v[126:127], v[36:37], 0 op_sel_hi:[0,1,0]
	v_cndmask_b32_e32 v4, v213, v4, vcc
	v_lshlrev_b32_e32 v4, 2, v4
	ds_bpermute_b32 v33, v4, v32
	v_pk_fma_f32 v[118:119], v[126:127], v[42:43], 0 op_sel_hi:[0,1,0]
	v_pk_fma_f32 v[122:123], v[126:127], v[40:41], 0 op_sel_hi:[0,1,0]
	v_and_b32_e32 v5, 0xffff0000, v147
	v_lshlrev_b32_e32 v4, 16, v147
	s_waitcnt lgkmcnt(0)
	v_or_b32_e32 v32, v33, v32
	v_add_u32_e32 v33, 0x200, v142
	ds_read2_b32 v[136:137], v33 offset1:129
	v_readfirstlane_b32 s4, v32
	v_mul_lo_u32 v32, v100, s24
	v_or_b32_e32 v32, v32, v152
	v_lshl_add_u32 v146, v32, 1, v221
	v_sub_u32_e64 v32, s15, 8 clamp
	v_mov_b32_e32 v7, v60
	s_mov_b32 s97, 1
	s_and_b32 s95, s4, s5
	v_readfirstlane_b32 s94, v32
	s_sub_i32 s17, 23, s17
	v_add_u32_e32 v145, 0, v145
	s_mov_b32 s50, 0
	v_mov_b32_e32 v150, 0xf149f2ca
	v_mov_b32_e32 v147, 0
	v_mov_b32_e32 v149, 0xf149f2ca
	v_mov_b32_e32 v151, 0
	v_mov_b32_e32 v48, 0
	v_mov_b32_e32 v49, v148
	v_mov_b32_e32 v50, v148
	v_mov_b32_e32 v51, v148
	v_mov_b32_e32 v36, 0
	v_mov_b32_e32 v37, v148
	v_mov_b32_e32 v38, v148
	v_mov_b32_e32 v39, v148
	v_mov_b32_e32 v40, 0
	v_mov_b32_e32 v41, v148
	v_mov_b32_e32 v42, v148
	v_mov_b32_e32 v43, v148
	v_mov_b32_e32 v32, 0
	v_mov_b32_e32 v33, v148
	v_mov_b32_e32 v34, v148
	v_mov_b32_e32 v35, v148
	v_mov_b32_e32 v60, 0
	v_mov_b32_e32 v61, v148
	v_mov_b32_e32 v62, v148
	v_mov_b32_e32 v63, v148
	v_mov_b32_e32 v52, 0
	v_mov_b32_e32 v53, v148
	v_mov_b32_e32 v54, v148
	v_mov_b32_e32 v55, v148
	v_mov_b32_e32 v56, 0
	v_mov_b32_e32 v57, v148
	v_mov_b32_e32 v58, v148
	v_mov_b32_e32 v59, v148
	v_mov_b32_e32 v44, 0
	v_mov_b32_e32 v45, v148
	v_mov_b32_e32 v46, v148
	v_mov_b32_e32 v47, v148
	v_readfirstlane_b32 s100, v210
	s_mov_b32 s98, 0
	s_waitcnt vmcnt(1)
	ds_write_b128 v139, v[24:27]
	s_waitcnt vmcnt(0)
	ds_write_b16 v146, v28
	ds_write_b16_d16_hi v146, v28 offset:144
	ds_write_b16 v146, v29 offset:288
	ds_write_b16_d16_hi v146, v29 offset:432
	ds_write_b16 v146, v30 offset:576
	ds_write_b16_d16_hi v146, v30 offset:720
	ds_write_b16 v146, v31 offset:864
	ds_write_b16_d16_hi v146, v31 offset:1008
	s_lshr_b32 s100, s100, 8
	s_mul_i32 s100, s100, 3
	s_cmp_eq_u32 s100, 3
	s_cbranch_scc0 .Lpr_skip
	s_setprio 1
.Lpr_skip:
	s_waitcnt lgkmcnt(0)
	s_barrier
